# grid barrier: waiters poll the cross-XCD arrival counter (TOP >= (gen+1)*nx); XCD-last adds to TOP without return; no release word
# speedup vs baseline: 1.0008x; 1.0002x over previous
.LBB0_90:
	v_readlane_b32 s4, v254, 5
	s_lshl_b32 s4, s4, 8
	v_readlane_b32 s6, v254, 3
	v_readlane_b32 s7, v254, 4
	s_add_u32 s4, s6, s4
	s_addc_u32 s5, s7, 0
	v_mov_b32_e32 v1, 0x1000
	v_mov_b32_e32 v3, 1
	global_atomic_add v3, v1, v3, s[4:5] offset:1024 sc0
	buffer_inv sc1
	v_cvt_f32_u32_e32 v1, v2
	v_sub_u32_e32 v4, 0, v2
	v_rcp_iflag_f32_e32 v1, v1
	s_nop 0
	v_mul_f32_e32 v1, 0x4f7ffffe, v1
	v_cvt_u32_f32_e32 v1, v1
	v_mul_lo_u32 v4, v4, v1
	v_mul_hi_u32 v4, v1, v4
	v_add_u32_e32 v1, v1, v4
	s_waitcnt vmcnt(1)
	v_mul_hi_u32 v1, v3, v1
	v_mul_lo_u32 v4, v1, v2
	v_sub_u32_e32 v4, v3, v4
	v_add_u32_e32 v5, 1, v1
	v_cmp_ge_u32_e32 vcc, v4, v2
	v_add_u32_e32 v3, 1, v3
	s_nop 0
	v_cndmask_b32_e32 v1, v1, v5, vcc
	v_sub_u32_e32 v5, v4, v2
	v_cndmask_b32_e32 v4, v4, v5, vcc
	v_add_u32_e32 v5, 1, v1
	v_cmp_ge_u32_e32 vcc, v4, v2
	s_nop 1
	v_cndmask_b32_e32 v1, v1, v5, vcc
	v_mul_lo_u32 v4, v2, v1
	v_add_u32_e32 v2, v4, v2
	v_cmp_eq_u32_e32 vcc, v3, v2
	s_add_u32 s98, s28, 0x7400
	s_addc_u32 s99, s29, 0
	s_and_saveexec_b64 s[6:7], vcc
	s_cbranch_execz .Lxb0_arr
	buffer_wbl2 sc1
	s_waitcnt vmcnt(0)
	v_mov_b32_e32 v4, 0
	v_mov_b32_e32 v5, 1
	global_atomic_add v4, v5, s[98:99]
.Lxb0_arr:
	s_or_b64 exec, exec, s[6:7]
	s_waitcnt lgkmcnt(0)
	v_add_u32_e32 v6, 1, v1
	v_mul_lo_u32 v6, v6, v0
	v_mov_b32_e32 v4, 0
	s_mov_b32 s100, 0
.Lxb0_poll:
	global_load_dword v5, v4, s[98:99] sc1
	s_waitcnt vmcnt(0)
	v_cmp_ge_u32_e32 vcc, v5, v6
	s_cbranch_vccnz .Lxb0_done
	s_sleep 1
	s_add_i32 s100, s100, 1
	s_cmp_lt_u32 s100, 0x4000
	s_cbranch_scc1 .Lxb0_poll
.Lxb0_done:
.LBB0_122:
	s_or_b64 exec, exec, s[2:3]
	s_waitcnt lgkmcnt(0)
	s_barrier
